# solo context-attention finish: sub-LN gain loads prefetched (was 16 load-wait-store rounds)
# speedup vs baseline: 1.0097x; 1.0069x over previous
.LBB0_1029:
	global_load_dwordx4 v[88:91], v[164:165], off
	v_lshl_add_u64 v[92:93], v[162:163], 0, s[34:35]
	v_add_co_u32_e32 v208, vcc, s52, v92
	s_waitcnt vmcnt(6)
	v_mfma_f32_32x32x16_bf16 v[64:79], v[64:67], v[104:107], 0
	v_addc_co_u32_e32 v209, vcc, 0, v93, vcc
	v_add_co_u32_e32 v92, vcc, s53, v92
	s_cmpk_lg_u32 s34, 0xe000
	s_nop 0
	v_addc_co_u32_e32 v93, vcc, 0, v93, vcc
	global_load_dwordx4 v[180:183], v[92:93], off offset:-4096
	global_load_dwordx4 v[184:187], v[208:209], off offset:1024
	global_load_dwordx4 v[188:191], v[208:209], off offset:2048
	global_load_dwordx4 v[192:195], v[92:93], off
	global_load_dwordx4 v[196:199], v[92:93], off offset:1024
	global_load_dwordx4 v[200:203], v[92:93], off offset:2048
	global_load_dwordx4 v[204:207], v[92:93], off offset:3072
	s_waitcnt vmcnt(12)
	v_mfma_f32_32x32x16_bf16 v[64:79], v[84:87], v[108:111], v[64:79]
	s_cselect_b32 s8, s36, 0x3800
	v_lshl_add_u64 v[164:165], s[8:9], 1, v[156:157]
	v_add_co_u32_e32 v210, vcc, s41, v164
	s_add_u32 s34, s34, 0x2000
	s_nop 0
	v_addc_co_u32_e32 v211, vcc, 0, v165, vcc
	s_waitcnt vmcnt(11)
	v_mfma_f32_32x32x16_bf16 v[64:79], v[80:83], v[120:123], v[64:79]
	s_addc_u32 s35, s35, 0
	s_addk_i32 s36, 0x800
	s_cmp_lg_u32 s34, 0x10000
	v_mfma_f32_32x32x16_bf16 v[64:79], v[128:131], v[124:127], v[64:79]
	global_load_dwordx4 v[128:131], v[210:211], off offset:3072
	s_waitcnt vmcnt(8)
	v_mfma_f32_32x32x16_bf16 v[80:95], v[88:91], v[116:119], 0
	s_nop 8
	v_fmamk_f32 v64, v64, 0x3e38aa3b, v153
	v_fmamk_f32 v65, v65, 0x3e38aa3b, v153
	v_fmamk_f32 v66, v66, 0x3e38aa3b, v153
	v_fmamk_f32 v67, v67, 0x3e38aa3b, v153
	v_fmamk_f32 v68, v68, 0x3e38aa3b, v153
	v_fmamk_f32 v69, v69, 0x3e38aa3b, v153
	v_fmamk_f32 v70, v70, 0x3e38aa3b, v153
	v_mfma_f32_32x32x16_bf16 v[80:95], v[140:143], v[112:115], v[80:95]
	v_fmamk_f32 v71, v71, 0x3e38aa3b, v153
	v_exp_f32_e32 v64, v64
	v_exp_f32_e32 v65, v65
	v_exp_f32_e32 v66, v66
	v_exp_f32_e32 v67, v67
	v_exp_f32_e32 v68, v68
	v_exp_f32_e32 v69, v69
	v_mfma_f32_32x32x16_bf16 v[80:95], v[136:139], v[96:99], v[80:95]
	v_exp_f32_e32 v70, v70
	v_exp_f32_e32 v71, v71
	v_fmamk_f32 v72, v72, 0x3e38aa3b, v153
	v_fmamk_f32 v73, v73, 0x3e38aa3b, v153
	v_fmamk_f32 v74, v74, 0x3e38aa3b, v153
	v_fmamk_f32 v75, v75, 0x3e38aa3b, v153
	v_fmamk_f32 v76, v76, 0x3e38aa3b, v153
	v_mfma_f32_32x32x16_bf16 v[80:95], v[132:135], v[100:103], v[80:95]
	v_fmamk_f32 v77, v77, 0x3e38aa3b, v153
	v_fmamk_f32 v78, v78, 0x3e38aa3b, v153
	v_fmamk_f32 v79, v79, 0x3e38aa3b, v153
	v_exp_f32_e32 v72, v72
	v_exp_f32_e32 v73, v73
	v_exp_f32_e32 v74, v74
	v_exp_f32_e32 v75, v75
	s_nop 4
	v_fmamk_f32 v80, v80, 0x3e38aa3b, v151
	v_fmamk_f32 v81, v81, 0x3e38aa3b, v151
	v_fmamk_f32 v82, v82, 0x3e38aa3b, v151
	v_fmamk_f32 v83, v83, 0x3e38aa3b, v151
	v_fmamk_f32 v84, v84, 0x3e38aa3b, v151
	v_fmamk_f32 v85, v85, 0x3e38aa3b, v151
	v_fmamk_f32 v86, v86, 0x3e38aa3b, v151
	v_fmamk_f32 v87, v87, 0x3e38aa3b, v151
	v_exp_f32_e32 v80, v80
	v_exp_f32_e32 v81, v81
	v_exp_f32_e32 v82, v82
	v_exp_f32_e32 v83, v83
	v_exp_f32_e32 v84, v84
	v_exp_f32_e32 v85, v85
	v_exp_f32_e32 v86, v86
	v_exp_f32_e32 v87, v87
	v_exp_f32_e32 v76, v76
	v_exp_f32_e32 v77, v77
	v_exp_f32_e32 v78, v78
	v_exp_f32_e32 v79, v79
	v_pk_mul_f32 v[64:65], v[160:161], v[64:65]
	v_pk_mul_f32 v[66:67], v[160:161], v[66:67]
	v_pk_mul_f32 v[68:69], v[160:161], v[68:69]
	v_pk_mul_f32 v[70:71], v[160:161], v[70:71]
	v_pk_fma_f32 v[64:65], v[158:159], v[80:81], v[64:65] neg_lo:[0,0,1] neg_hi:[0,0,1]
	v_pk_fma_f32 v[66:67], v[158:159], v[82:83], v[66:67] neg_lo:[0,0,1] neg_hi:[0,0,1]
	v_pk_fma_f32 v[68:69], v[158:159], v[84:85], v[68:69] neg_lo:[0,0,1] neg_hi:[0,0,1]
	v_pk_fma_f32 v[70:71], v[158:159], v[86:87], v[70:71] neg_lo:[0,0,1] neg_hi:[0,0,1]
	v_cvt_pk_bf16_f32 v64, v64, v65
	v_cvt_pk_bf16_f32 v65, v66, v67
	v_cvt_pk_bf16_f32 v66, v68, v69
	v_cvt_pk_bf16_f32 v67, v70, v71
	v_pk_mul_f32 v[68:69], v[160:161], v[72:73]
	v_pk_mul_f32 v[70:71], v[160:161], v[74:75]
	v_pk_mul_f32 v[72:73], v[160:161], v[76:77]
	v_pk_mul_f32 v[74:75], v[160:161], v[78:79]
	v_fmamk_f32 v76, v88, 0x3e38aa3b, v151
	v_fmamk_f32 v77, v89, 0x3e38aa3b, v151
	v_fmamk_f32 v78, v90, 0x3e38aa3b, v151
	v_fmamk_f32 v79, v91, 0x3e38aa3b, v151
	v_fmamk_f32 v80, v92, 0x3e38aa3b, v151
	v_fmamk_f32 v81, v93, 0x3e38aa3b, v151
	v_fmamk_f32 v82, v94, 0x3e38aa3b, v151
	v_fmamk_f32 v83, v95, 0x3e38aa3b, v151
	v_exp_f32_e32 v76, v76
	v_exp_f32_e32 v77, v77
	v_exp_f32_e32 v78, v78
	v_exp_f32_e32 v79, v79
	v_exp_f32_e32 v80, v80
	v_exp_f32_e32 v81, v81
	v_exp_f32_e32 v82, v82
	v_exp_f32_e32 v83, v83
	s_waitcnt vmcnt(7)
	v_mfma_f32_32x32x16_bf16 v[48:63], v[180:183], v[64:67], v[48:63]
	v_fma_f32 v68, v158, v76, -v68
	v_fma_f32 v69, v159, v77, -v69
	v_cvt_pk_bf16_f32 v68, v68, v69
	s_waitcnt vmcnt(5)
	v_mfma_f32_32x32x16_bf16 v[32:47], v[188:191], v[64:67], v[32:47]
	s_waitcnt vmcnt(4)
	v_mfma_f32_32x32x16_bf16 v[16:31], v[192:195], v[64:67], v[16:31]
	s_waitcnt vmcnt(2)
	v_mfma_f32_32x32x16_bf16 v[0:15], v[200:203], v[64:67], v[0:15]
	v_fma_f32 v64, v158, v78, -v70
	v_fma_f32 v65, v159, v79, -v71
	v_fma_f32 v66, v158, v80, -v72
	v_fma_f32 v67, v159, v81, -v73
	v_fma_f32 v72, v158, v82, -v74
	v_fma_f32 v73, v159, v83, -v75
	v_cvt_pk_bf16_f32 v69, v64, v65
	v_cvt_pk_bf16_f32 v70, v66, v67
	v_cvt_pk_bf16_f32 v71, v72, v73
	global_load_dwordx4 v[72:75], v[208:209], off offset:3072
	global_load_dwordx4 v[64:67], v[210:211], off
	global_load_dwordx4 v[84:87], v[210:211], off offset:1024
	global_load_dwordx4 v[80:83], v[210:211], off offset:2048
	global_load_dwordx4 v[140:143], v[164:165], off offset:1024
	global_load_dwordx4 v[136:139], v[164:165], off offset:2048
	global_load_dwordx4 v[132:135], v[164:165], off offset:3072
	v_mfma_f32_32x32x16_bf16 v[48:63], v[184:187], v[68:71], v[48:63]
	s_waitcnt vmcnt(6)
	v_mfma_f32_32x32x16_bf16 v[32:47], v[72:75], v[68:71], v[32:47]
	v_mfma_f32_32x32x16_bf16 v[16:31], v[196:199], v[68:71], v[16:31]
	v_mfma_f32_32x32x16_bf16 v[0:15], v[204:207], v[68:71], v[0:15]
	s_cbranch_scc1 .LBB0_1029
	s_load_dwordx2 s[34:35], s[20:21], 0x68
	s_nop 5
	v_mul_f32_e32 v78, v49, v49
	v_lshlrev_b32_e32 v79, 2, v146
	v_fmac_f32_e32 v78, v48, v48
	v_fmac_f32_e32 v78, v50, v50
	s_waitcnt lgkmcnt(0)
	global_load_dwordx4 v[66:69], v79, s[34:35]
	global_load_dwordx4 v[180:183], v79, s[34:35] offset:32
	global_load_dwordx4 v[184:187], v79, s[34:35] offset:64
	global_load_dwordx4 v[188:191], v79, s[34:35] offset:96
	global_load_dwordx4 v[192:195], v79, s[34:35] offset:128
	global_load_dwordx4 v[196:199], v79, s[34:35] offset:160
	global_load_dwordx4 v[200:203], v79, s[34:35] offset:192
	global_load_dwordx4 v[204:207], v79, s[34:35] offset:224
	global_load_dwordx4 v[208:211], v79, s[34:35] offset:256
	global_load_dwordx4 v[212:215], v79, s[34:35] offset:288
	global_load_dwordx4 v[216:219], v79, s[34:35] offset:320
	global_load_dwordx4 v[220:223], v79, s[34:35] offset:352
	global_load_dwordx4 v[224:227], v79, s[34:35] offset:384
	global_load_dwordx4 v[228:231], v79, s[34:35] offset:416
	global_load_dwordx4 v[92:95], v79, s[34:35] offset:448
	global_load_dwordx4 v[96:99], v79, s[34:35] offset:480
	v_fmac_f32_e32 v78, v51, v51
	v_fmac_f32_e32 v78, v52, v52
	v_fmac_f32_e32 v78, v53, v53
	v_fmac_f32_e32 v78, v54, v54
	v_fmac_f32_e32 v78, v55, v55
	v_fmac_f32_e32 v78, v56, v56
	v_fmac_f32_e32 v78, v57, v57
	v_fmac_f32_e32 v78, v58, v58
	v_fmac_f32_e32 v78, v59, v59
	v_fmac_f32_e32 v78, v60, v60
	v_fmac_f32_e32 v78, v61, v61
	v_fmac_f32_e32 v78, v62, v62
	v_fmac_f32_e32 v78, v63, v63
	v_fmac_f32_e32 v78, v32, v32
	v_fmac_f32_e32 v78, v33, v33
	v_fmac_f32_e32 v78, v34, v34
	v_fmac_f32_e32 v78, v35, v35
	v_fmac_f32_e32 v78, v36, v36
	v_fmac_f32_e32 v78, v37, v37
	v_fmac_f32_e32 v78, v38, v38
	v_fmac_f32_e32 v78, v39, v39
	v_fmac_f32_e32 v78, v40, v40
	v_fmac_f32_e32 v78, v41, v41
	v_fmac_f32_e32 v78, v42, v42
	v_fmac_f32_e32 v78, v43, v43
	v_fmac_f32_e32 v78, v44, v44
	v_fmac_f32_e32 v78, v45, v45
	v_fmac_f32_e32 v78, v46, v46
	v_fmac_f32_e32 v78, v47, v47
	v_fmac_f32_e32 v78, v16, v16
	v_fmac_f32_e32 v78, v17, v17
	v_fmac_f32_e32 v78, v18, v18
	v_fmac_f32_e32 v78, v19, v19
	v_fmac_f32_e32 v78, v20, v20
	v_fmac_f32_e32 v78, v21, v21
	v_fmac_f32_e32 v78, v22, v22
	v_fmac_f32_e32 v78, v23, v23
	v_fmac_f32_e32 v78, v24, v24
	v_fmac_f32_e32 v78, v25, v25
	v_fmac_f32_e32 v78, v26, v26
	v_fmac_f32_e32 v78, v27, v27
	v_fmac_f32_e32 v78, v28, v28
	v_fmac_f32_e32 v78, v29, v29
	v_fmac_f32_e32 v78, v30, v30
	v_fmac_f32_e32 v78, v31, v31
	v_fmac_f32_e32 v78, v0, v0
	v_fmac_f32_e32 v78, v1, v1
	v_fmac_f32_e32 v78, v2, v2
	v_fmac_f32_e32 v78, v3, v3
	v_fmac_f32_e32 v78, v4, v4
	v_fmac_f32_e32 v78, v5, v5
	v_pk_mul_f32 v[76:77], v[6:7], v[6:7]
	v_pk_mul_f32 v[74:75], v[8:9], v[8:9]
	v_add_f32_e32 v76, v76, v78
	v_add_f32_e32 v76, v77, v76
	v_add_f32_e32 v74, v74, v76
	v_pk_mul_f32 v[72:73], v[10:11], v[10:11]
	v_add_f32_e32 v74, v75, v74
	v_add_f32_e32 v72, v72, v74
	v_pk_mul_f32 v[70:71], v[12:13], v[12:13]
	v_add_f32_e32 v72, v73, v72
	v_add_f32_e32 v70, v70, v72
	s_waitcnt vmcnt(21)
	v_pk_mul_f32 v[64:65], v[14:15], v[14:15]
	v_add_f32_e32 v70, v71, v70
	v_add_f32_e32 v64, v64, v70
	v_add_f32_e32 v64, v65, v64
	ds_bpermute_b32 v65, v171, v64
	s_lshl_b32 s8, s37, 1
	s_waitcnt lgkmcnt(0)
	v_add_f32_e32 v64, v64, v65
	v_fmamk_f32 v64, v64, 0x3c000000, v178
	v_mul_f32_e32 v65, 0x4b800000, v64
	v_cmp_gt_f32_e32 vcc, s54, v64
	s_nop 1
	v_cndmask_b32_e32 v64, v64, v65, vcc
	v_rsq_f32_e32 v64, v64
	s_nop 0
	v_mul_f32_e32 v65, 0x45800000, v64
	v_cndmask_b32_e32 v64, v64, v65, vcc
	v_mul_f32_e32 v64, 0x3f4ccccd, v64
	v_pk_mul_f32 v[48:49], v[48:49], v[64:65] op_sel_hi:[1,0]
	v_pk_mul_f32 v[50:51], v[50:51], v[64:65] op_sel_hi:[1,0]
	s_waitcnt vmcnt(15)
	v_pk_mul_f32 v[48:49], v[66:67], v[48:49]
	v_pk_mul_f32 v[50:51], v[68:69], v[50:51]
	v_cvt_pk_bf16_f32 v48, v48, v49
	v_cvt_pk_bf16_f32 v49, v50, v51
	v_lshlrev_b64 v[50:51], 11, v[154:155]
	v_lshl_add_u64 v[50:51], s[30:31], 0, v[50:51]
	v_lshl_add_u64 v[50:51], v[50:51], 0, s[8:9]
	v_lshlrev_b32_e32 v66, 1, v146
	v_mov_b32_e32 v67, v145
	v_lshl_add_u64 v[66:67], v[50:51], 0, v[66:67]
	v_add_co_u32_e32 v50, vcc, s55, v66
	v_pk_mul_f32 v[52:53], v[52:53], v[64:65] op_sel_hi:[1,0]
	s_nop 0
	v_addc_co_u32_e32 v51, vcc, 0, v67, vcc
	global_store_dwordx2 v[50:51], v[48:49], off
	v_pk_mul_f32 v[54:55], v[54:55], v[64:65] op_sel_hi:[1,0]
	v_lshl_add_u64 v[66:67], v[66:67], 0, s[28:29]
	v_pk_mul_f32 v[32:33], v[32:33], v[64:65] op_sel_hi:[1,0]
	v_pk_mul_f32 v[34:35], v[34:35], v[64:65] op_sel_hi:[1,0]
	v_pk_mul_f32 v[36:37], v[36:37], v[64:65] op_sel_hi:[1,0]
	v_pk_mul_f32 v[38:39], v[38:39], v[64:65] op_sel_hi:[1,0]
	v_pk_mul_f32 v[16:17], v[16:17], v[64:65] op_sel_hi:[1,0]
	v_pk_mul_f32 v[18:19], v[18:19], v[64:65] op_sel_hi:[1,0]
	v_pk_mul_f32 v[20:21], v[20:21], v[64:65] op_sel_hi:[1,0]
	v_pk_mul_f32 v[22:23], v[22:23], v[64:65] op_sel_hi:[1,0]
	v_pk_mul_f32 v[0:1], v[0:1], v[64:65] op_sel_hi:[1,0]
	v_pk_mul_f32 v[2:3], v[2:3], v[64:65] op_sel_hi:[1,0]
	v_pk_mul_f32 v[4:5], v[4:5], v[64:65] op_sel_hi:[1,0]
	v_pk_mul_f32 v[6:7], v[6:7], v[64:65] op_sel_hi:[1,0]
	s_waitcnt vmcnt(15)
	v_mov_b64_e32 v[48:49], v[180:181]
	v_mov_b64_e32 v[50:51], v[182:183]
	v_pk_mul_f32 v[48:49], v[48:49], v[52:53]
	v_pk_mul_f32 v[50:51], v[50:51], v[54:55]
	v_cvt_pk_bf16_f32 v48, v48, v49
	v_cvt_pk_bf16_f32 v49, v50, v51
	global_store_dwordx2 v[66:67], v[48:49], off offset:16
	v_pk_mul_f32 v[52:53], v[56:57], v[64:65] op_sel_hi:[1,0]
	v_pk_mul_f32 v[54:55], v[58:59], v[64:65] op_sel_hi:[1,0]
	s_waitcnt vmcnt(15)
	v_mov_b64_e32 v[48:49], v[184:185]
	v_mov_b64_e32 v[50:51], v[186:187]
	v_pk_mul_f32 v[48:49], v[48:49], v[52:53]
	v_pk_mul_f32 v[50:51], v[50:51], v[54:55]
	v_cvt_pk_bf16_f32 v48, v48, v49
	v_cvt_pk_bf16_f32 v49, v50, v51
	global_store_dwordx2 v[66:67], v[48:49], off offset:32
	v_pk_mul_f32 v[52:53], v[60:61], v[64:65] op_sel_hi:[1,0]
	v_pk_mul_f32 v[54:55], v[62:63], v[64:65] op_sel_hi:[1,0]
	s_waitcnt vmcnt(15)
	v_mov_b64_e32 v[48:49], v[188:189]
	v_mov_b64_e32 v[50:51], v[190:191]
	v_pk_mul_f32 v[48:49], v[48:49], v[52:53]
	v_pk_mul_f32 v[50:51], v[50:51], v[54:55]
	v_cvt_pk_bf16_f32 v48, v48, v49
	v_cvt_pk_bf16_f32 v49, v50, v51
	global_store_dwordx2 v[66:67], v[48:49], off offset:48
	s_waitcnt vmcnt(15)
	v_mov_b64_e32 v[48:49], v[192:193]
	v_mov_b64_e32 v[50:51], v[194:195]
	v_pk_mul_f32 v[32:33], v[48:49], v[32:33]
	v_pk_mul_f32 v[34:35], v[50:51], v[34:35]
	v_cvt_pk_bf16_f32 v32, v32, v33
	v_cvt_pk_bf16_f32 v33, v34, v35
	global_store_dwordx2 v[66:67], v[32:33], off offset:64
	s_waitcnt vmcnt(15)
	v_mov_b64_e32 v[32:33], v[196:197]
	v_mov_b64_e32 v[34:35], v[198:199]
	v_pk_mul_f32 v[32:33], v[36:37], v[32:33]
	v_pk_mul_f32 v[34:35], v[38:39], v[34:35]
	v_cvt_pk_bf16_f32 v32, v32, v33
	v_cvt_pk_bf16_f32 v33, v34, v35
	global_store_dwordx2 v[66:67], v[32:33], off offset:80
	v_pk_mul_f32 v[36:37], v[40:41], v[64:65] op_sel_hi:[1,0]
	v_pk_mul_f32 v[38:39], v[42:43], v[64:65] op_sel_hi:[1,0]
	s_waitcnt vmcnt(15)
	v_mov_b64_e32 v[32:33], v[200:201]
	v_mov_b64_e32 v[34:35], v[202:203]
	v_pk_mul_f32 v[32:33], v[36:37], v[32:33]
	v_pk_mul_f32 v[34:35], v[38:39], v[34:35]
	v_cvt_pk_bf16_f32 v32, v32, v33
	v_cvt_pk_bf16_f32 v33, v34, v35
	global_store_dwordx2 v[66:67], v[32:33], off offset:96
	v_pk_mul_f32 v[36:37], v[44:45], v[64:65] op_sel_hi:[1,0]
	v_pk_mul_f32 v[38:39], v[46:47], v[64:65] op_sel_hi:[1,0]
	s_waitcnt vmcnt(15)
	v_mov_b64_e32 v[32:33], v[204:205]
	v_mov_b64_e32 v[34:35], v[206:207]
	v_pk_mul_f32 v[32:33], v[36:37], v[32:33]
	v_pk_mul_f32 v[34:35], v[38:39], v[34:35]
	v_cvt_pk_bf16_f32 v32, v32, v33
	v_cvt_pk_bf16_f32 v33, v34, v35
	global_store_dwordx2 v[66:67], v[32:33], off offset:112
	s_waitcnt vmcnt(15)
	v_mov_b64_e32 v[32:33], v[208:209]
	v_mov_b64_e32 v[34:35], v[210:211]
	v_pk_mul_f32 v[16:17], v[16:17], v[32:33]
	v_pk_mul_f32 v[18:19], v[18:19], v[34:35]
	v_cvt_pk_bf16_f32 v16, v16, v17
	v_cvt_pk_bf16_f32 v17, v18, v19
	global_store_dwordx2 v[66:67], v[16:17], off offset:128
	s_waitcnt vmcnt(15)
	v_mov_b64_e32 v[16:17], v[212:213]
	v_mov_b64_e32 v[18:19], v[214:215]
	v_pk_mul_f32 v[16:17], v[20:21], v[16:17]
	v_pk_mul_f32 v[18:19], v[22:23], v[18:19]
	v_cvt_pk_bf16_f32 v16, v16, v17
	v_cvt_pk_bf16_f32 v17, v18, v19
	global_store_dwordx2 v[66:67], v[16:17], off offset:144
	v_pk_mul_f32 v[20:21], v[24:25], v[64:65] op_sel_hi:[1,0]
	v_pk_mul_f32 v[22:23], v[26:27], v[64:65] op_sel_hi:[1,0]
	s_waitcnt vmcnt(15)
	v_mov_b64_e32 v[16:17], v[216:217]
	v_mov_b64_e32 v[18:19], v[218:219]
	v_pk_mul_f32 v[16:17], v[20:21], v[16:17]
	v_pk_mul_f32 v[18:19], v[22:23], v[18:19]
	v_cvt_pk_bf16_f32 v16, v16, v17
	v_cvt_pk_bf16_f32 v17, v18, v19
	global_store_dwordx2 v[66:67], v[16:17], off offset:160
	v_pk_mul_f32 v[20:21], v[28:29], v[64:65] op_sel_hi:[1,0]
	v_pk_mul_f32 v[22:23], v[30:31], v[64:65] op_sel_hi:[1,0]
	s_waitcnt vmcnt(15)
	v_mov_b64_e32 v[16:17], v[220:221]
	v_mov_b64_e32 v[18:19], v[222:223]
	v_pk_mul_f32 v[16:17], v[20:21], v[16:17]
	v_pk_mul_f32 v[18:19], v[22:23], v[18:19]
	v_cvt_pk_bf16_f32 v16, v16, v17
	v_cvt_pk_bf16_f32 v17, v18, v19
	global_store_dwordx2 v[66:67], v[16:17], off offset:176
	s_waitcnt vmcnt(15)
	v_mov_b64_e32 v[16:17], v[224:225]
	v_mov_b64_e32 v[18:19], v[226:227]
	v_pk_mul_f32 v[0:1], v[0:1], v[16:17]
	v_pk_mul_f32 v[2:3], v[2:3], v[18:19]
	v_cvt_pk_bf16_f32 v0, v0, v1
	v_cvt_pk_bf16_f32 v1, v2, v3
	global_store_dwordx2 v[66:67], v[0:1], off offset:192
	s_waitcnt vmcnt(15)
	v_mov_b64_e32 v[0:1], v[228:229]
	v_mov_b64_e32 v[2:3], v[230:231]
	v_pk_mul_f32 v[0:1], v[4:5], v[0:1]
	v_pk_mul_f32 v[2:3], v[6:7], v[2:3]
	v_cvt_pk_bf16_f32 v0, v0, v1
	v_cvt_pk_bf16_f32 v1, v2, v3
	global_store_dwordx2 v[66:67], v[0:1], off offset:208
	v_pk_mul_f32 v[4:5], v[8:9], v[64:65] op_sel_hi:[1,0]
	v_pk_mul_f32 v[6:7], v[10:11], v[64:65] op_sel_hi:[1,0]
	s_waitcnt vmcnt(15)
	v_mov_b64_e32 v[0:1], v[92:93]
	v_mov_b64_e32 v[2:3], v[94:95]
	v_pk_mul_f32 v[0:1], v[4:5], v[0:1]
	v_pk_mul_f32 v[2:3], v[6:7], v[2:3]
	v_cvt_pk_bf16_f32 v0, v0, v1
	v_cvt_pk_bf16_f32 v1, v2, v3
	global_store_dwordx2 v[66:67], v[0:1], off offset:224
	v_pk_mul_f32 v[4:5], v[12:13], v[64:65] op_sel_hi:[1,0]
	v_pk_mul_f32 v[6:7], v[14:15], v[64:65] op_sel_hi:[1,0]
	s_waitcnt vmcnt(15)
	v_mov_b64_e32 v[0:1], v[96:97]
	v_mov_b64_e32 v[2:3], v[98:99]
	v_pk_mul_f32 v[0:1], v[4:5], v[0:1]
	v_pk_mul_f32 v[2:3], v[6:7], v[2:3]
	v_cvt_pk_bf16_f32 v0, v0, v1
	v_cvt_pk_bf16_f32 v1, v2, v3
	global_store_dwordx2 v[66:67], v[0:1], off offset:240
	s_branch .LBB0_1004
